# P7c: gathers via LDS-DMA ring (no VGPR staging/ds_write), index+coefficient rows staged via LDS-DMA (1KB less VMEM return per token), coefficient exchange removed
# speedup vs baseline: 1.0094x; 1.0094x over previous
; #define P7C_LOADA(R0, R1, C, S, X, t) do { const int tt_ = (t) < NT_TOK ? (t) : NT_TOK - 1; const unsigned char* rp_ = rp0 + (size_t)tt_ * 256; R0 = *(const v4u*)rp_; R1 = *(const v4u*)(rp_ + 16); \
;             C = *(const v4u*)(cp0 + (size_t)tt_ * 128); S = SCQ[tt_]; X = *(const unsigned*)(X2Bw + (size_t)tt_ * DM + 128 * hs + 16 * seg + 2 * r); } while (0)
; #define P7C_ISSUE(G, R0, R1) do { __builtin_amdgcn_s_setprio(3); _Pragma("unroll") for (int i_ = 0; i_ < 16; ++i_) { const unsigned e_ = P7_EID(R0, R1, i_); G[i_] = *(const v4u*)(Vb + (size_t)e_ * 128); } __builtin_amdgcn_s_setprio(0); } while (0)
; __device__ __forceinline__ void p7c_vaxpy(Frame& F, unsigned* bar, unsigned x, unsigned rank) {
;     ...
;     for (int pass = 0; pass < 16; ++pass) {
;         const int hs = (2 * (int)so.vx + pass) & 15; if ((unsigned)(hs >> 1) % so.npop != so.vx) continue;
;         const unsigned char* Vb = F.ws + WS_V + (size_t)hs * (16384 * 128) + 16 * seg;
;         const unsigned char* rp0 = RE16b + r * 32; const unsigned char* cp0 = CQb + r * 16;
;     ...
;         v4u GA[16], GB[16], ra0, ra1, ca, rb0, rb1, cb, cA, cB; float sa, sb, sA, sB; unsigned xa, xb2, xA, xB;
;         P7C_LOADA(ra0, ra1, ca, sa, xa, gwl);
;         P7C_LOADA(rb0, rb1, cb, sb, xb2, gwl + stride);
;         P7C_ISSUE(GA, ra0, ra1); cA = ca; sA = sa; xA = xa;
.LBB0_1084:
	s_waitcnt vmcnt(23)
	v_add_u32_e32 v0, s22, v192
	v_bfe_u32 v1, v0, 1, 3
	v_mul_hi_u32 v2, v1, v193
	v_mul_lo_u32 v2, v2, v191
	v_sub_u32_e32 v1, v1, v2
	v_sub_u32_e32 v2, v1, v191
	v_cmp_ge_u32_e32 vcc, v1, v191
	s_nop 1
	v_cndmask_b32_e32 v1, v1, v2, vcc
	v_sub_u32_e32 v2, v1, v191
	v_cmp_ge_u32_e32 vcc, v1, v191
	s_nop 1
	v_cndmask_b32_e32 v1, v1, v2, vcc
	v_cmp_ne_u32_e32 vcc, v1, v190
	s_cbranch_vccnz .LBB0_1083
	v_and_b32_e32 v80, 15, v0
	v_lshlrev_b32_e32 v156, 21, v80
	v_lshl_add_u64 v[180:181], v[176:177], 0, v[156:157]
	s_nop 1
	v_readfirstlane_b32 s56, v180
	v_readfirstlane_b32 s57, v181
	s_movk_i32 s58, 0x80
	s_nop 3
	s_sub_u32 s56, s56, 0x80
	s_subb_u32 s57, s57, 0
	s_nop 3
	v_subrev_u32_e32 v200, s56, v180
	v_and_b32_e32 v12, 7, v231
	v_bfe_u32 v13, v231, 4, 1
	v_lshlrev_b32_e32 v14, 4, v12
	v_lshlrev_b32_e32 v13, 2, v13
	v_sub_u32_e32 v14, v200, v14
	v_xor_b32_e32 v12, v12, v13
	v_xor_b32_e32 v13, 1, v12
	v_lshl_add_u32 v201, v13, 4, v14
	v_xor_b32_e32 v13, 2, v12
	v_lshl_add_u32 v202, v13, 4, v14
	v_xor_b32_e32 v13, 3, v12
	v_lshl_add_u32 v203, v13, 4, v14
	v_lshl_add_u32 v200, v12, 4, v14
	v_readfirstlane_b32 s60, v158
	v_readfirstlane_b32 s61, v159
	v_readfirstlane_b32 s82, v160
	v_readfirstlane_b32 s83, v161
	v_readfirstlane_b32 s98, v164
	v_readfirstlane_b32 s99, v165
	v_readfirstlane_b32 s100, v168
	v_readfirstlane_b32 s101, v169
	v_readfirstlane_b32 s28, v170
	v_readfirstlane_b32 s29, v171
	s_lshr_b32 s59, s97, 4
	s_add_i32 s59, s59, 0x21000
	v_lshlrev_b32_e32 v16, 2, v231
	v_lshrrev_b32_e32 v17, 3, v231
	v_lshlrev_b32_e32 v18, 4, v17
	v_and_b32_e32 v18, 0xffffffef, v18
	v_add_u32_e32 v18, s59, v18
	v_lshl_add_u32 v17, v17, 5, s59
	v_lshlrev_b32_e32 v156, 8, v80
	global_load_dwordx4 v[24:27], v[162:163], off offset:16
	global_load_dwordx4 v[8:11], v[162:163], off
	s_waitcnt vmcnt(4)
	v_lshl_add_u64 v[12:13], v[166:167], 0, v[156:157]
	s_add_i32 m0, s59, 0x100
	s_nop 0
	global_load_lds_dword v16, s[98:99]
	s_add_i32 m0, s59, 0x200
	s_nop 0
	global_load_lds_dword v16, s[100:101]
	s_add_i32 m0, s59, 0x300
	s_nop 0
	global_load_lds_dword v16, s[28:29]
	v_lshl_add_u64 v[14:15], v[172:173], 0, v[156:157]
	global_load_dword v196, v157, s[4:5]
	global_load_dword v197, v[12:13], off
	global_load_dword v198, v157, s[6:7]
	global_load_dword v199, v[14:15], off
	s_setprio 3
	s_waitcnt vmcnt(7)
	v_mad_u32_u16 v12, v8, s58, v200 op_sel:[0,0,0,0]
	v_mad_u32_u16 v14, v8, s58, v201 op_sel:[1,0,0,0]
	s_add_i32 m0, s97, 0x0
	s_nop 0
	global_load_lds_dwordx4 v12, s[56:57]
	s_add_i32 m0, s97, 0x400
	s_nop 0
	global_load_lds_dwordx4 v14, s[56:57]
	v_mad_u32_u16 v12, v9, s58, v202 op_sel:[0,0,0,0]
	v_mad_u32_u16 v8, v9, s58, v203 op_sel:[1,0,0,0]
	s_add_i32 m0, s97, 0x800
	s_nop 0
	global_load_lds_dwordx4 v12, s[56:57]
	s_add_i32 m0, s97, 0xc00
	s_nop 0
	global_load_lds_dwordx4 v8, s[56:57]
	v_mad_u32_u16 v8, v10, s58, v200 op_sel:[0,0,0,0]
	v_mad_u32_u16 v12, v10, s58, v201 op_sel:[1,0,0,0]
	s_add_i32 m0, s97, 0x1000
	s_nop 0
	global_load_lds_dwordx4 v8, s[56:57]
	s_add_i32 m0, s97, 0x1400
	s_nop 0
	global_load_lds_dwordx4 v12, s[56:57]
	v_mad_u32_u16 v8, v11, s58, v202 op_sel:[0,0,0,0]
	v_mad_u32_u16 v10, v11, s58, v203 op_sel:[1,0,0,0]
	s_add_i32 m0, s97, 0x1800
	s_nop 0
	global_load_lds_dwordx4 v8, s[56:57]
	s_add_i32 m0, s97, 0x1c00
	s_nop 0
	global_load_lds_dwordx4 v10, s[56:57]
	v_mad_u32_u16 v8, v24, s58, v200 op_sel:[0,0,0,0]
	v_mad_u32_u16 v10, v24, s58, v201 op_sel:[1,0,0,0]
	s_add_i32 m0, s97, 0x2000
	s_nop 0
	global_load_lds_dwordx4 v8, s[56:57]
	s_add_i32 m0, s97, 0x2400
	s_nop 0
	global_load_lds_dwordx4 v10, s[56:57]
	v_mad_u32_u16 v8, v25, s58, v202 op_sel:[0,0,0,0]
	v_mad_u32_u16 v10, v25, s58, v203 op_sel:[1,0,0,0]
	s_add_i32 m0, s97, 0x2800
	s_nop 0
	global_load_lds_dwordx4 v8, s[56:57]
	s_add_i32 m0, s97, 0x2c00
	s_nop 0
	global_load_lds_dwordx4 v10, s[56:57]
	v_mad_u32_u16 v8, v26, s58, v200 op_sel:[0,0,0,0]
	v_mad_u32_u16 v12, v26, s58, v201 op_sel:[1,0,0,0]
	v_mad_u32_u16 v24, v27, s58, v202 op_sel:[0,0,0,0]
	v_mad_u32_u16 v28, v27, s58, v203 op_sel:[1,0,0,0]
	s_add_i32 m0, s97, 0x3000
	s_nop 0
	global_load_lds_dwordx4 v8, s[56:57]
	s_nop 0
	s_add_i32 m0, s97, 0x3400
	s_nop 0
	global_load_lds_dwordx4 v12, s[56:57]
	s_nop 0
	s_add_i32 m0, s97, 0x3800
	s_nop 0
	global_load_lds_dwordx4 v24, s[56:57]
	s_nop 0
	s_add_i32 m0, s97, 0x3c00
	s_nop 0
	global_load_lds_dwordx4 v28, s[56:57]
	s_setprio 0
	s_andn2_b64 vcc, exec, s[8:9]
	s_cbranch_vccnz .LBB0_1083
	v_lshlrev_b32_e32 v81, 7, v80
	v_lshlrev_b32_e32 v156, 1, v81
	v_lshl_add_u64 v[182:183], v[174:175], 0, v[156:157]
	v_lshlrev_b32_e32 v156, 2, v80
	v_and_b32_e32 v80, 15, v195
	v_lshl_add_u64 v[184:185], s[2:3], 0, v[156:157]
	v_lshlrev_b32_e32 v156, 2, v80
	v_lshl_add_u64 v[186:187], s[12:13], 0, v[156:157]
	v_lshlrev_b32_e32 v156, 8, v80
	v_lshl_add_u64 v[188:189], v[178:179], 0, v[156:157]
	s_mov_b32 s20, s0
	s_branch .LBB0_1089

; #define P7C_LOADA(R0, R1, C, S, X, t) do { const int tt_ = (t) < NT_TOK ? (t) : NT_TOK - 1; const unsigned char* rp_ = rp0 + (size_t)tt_ * 256; R0 = *(const v4u*)rp_; R1 = *(const v4u*)(rp_ + 16); \
;             C = *(const v4u*)(cp0 + (size_t)tt_ * 128); S = SCQ[tt_]; X = *(const unsigned*)(X2Bw + (size_t)tt_ * DM + 128 * hs + 16 * seg + 2 * r); } while (0)
; #define P7C_ISSUE(G, R0, R1) do { __builtin_amdgcn_s_setprio(3); _Pragma("unroll") for (int i_ = 0; i_ < 16; ++i_) { const unsigned e_ = P7_EID(R0, R1, i_); G[i_] = *(const v4u*)(Vb + (size_t)e_ * 128); } __builtin_amdgcn_s_setprio(0); } while (0)
; __device__ __forceinline__ void p7c_vaxpy(Frame& F, unsigned* bar, unsigned x, unsigned rank) {
;     ...
;         v4u GA[16], GB[16], ra0, ra1, ca, rb0, rb1, cb, cA, cB; float sa, sb, sA, sB; unsigned xa, xb2, xA, xB;
;         P7C_LOADA(ra0, ra1, ca, sa, xa, gwl);
;         P7C_LOADA(rb0, rb1, cb, sb, xb2, gwl + stride);
;         P7C_ISSUE(GA, ra0, ra1); cA = ca; sA = sa; xA = xa;
; #pragma unroll 1
;         for (int t = gwl; t < NT_TOK; t += 2 * stride) {
;             P7C_LOADA(ra0, ra1, ca, sa, xa, t + 2 * stride); P7C_ISSUE(GB, rb0, rb1); cB = cb; sB = sb; xB = xb2; P7C_COMP(GA, cA, sA, xA, t);
;             P7C_LOADA(rb0, rb1, cb, sb, xb2, t + 3 * stride); P7C_ISSUE(GA, ra0, ra1); cA = ca; sA = sa; xA = xa; P7C_COMP(GB, cB, sB, xB, t + stride);
.LBB0_1088:
	s_waitcnt vmcnt(18) lgkmcnt(0)
	v_lshl_add_u64 v[186:187], v[186:187], 0, s[14:15]
	v_lshl_add_u64 v[188:189], v[188:189], 0, s[16:17]
	s_cmpk_lt_i32 s27, 0x6000
	s_waitcnt vmcnt(17)
	v_mov_b32_e32 v198, v207
	s_waitcnt vmcnt(16)
	v_mov_b32_e32 v199, v206
	s_mov_b32 s20, s27
	s_cbranch_scc0 .LBB0_1083
.LBB0_1089:
	s_add_i32 s27, s20, s10
	s_min_i32 s18, s27, 0x5fff
	s_ashr_i32 s19, s18, 31
	s_waitcnt vmcnt(22)
	ds_read_b128 v[220:223], v18 offset:256
	s_lshl_b64 s[28:29], s[18:19], 8
	ds_read_b128 v[224:227], v18 offset:272
	s_waitcnt lgkmcnt(0)
	s_add_i32 m0, s59, 0x0
	s_add_u32 s28, s28, s60
	s_addc_u32 s29, s29, s61
	global_load_lds_dword v16, s[28:29]
	s_lshl_b64 s[28:29], s[18:19], 7
	s_add_i32 m0, s59, 0x100
	s_add_u32 s28, s28, s82
	s_addc_u32 s29, s29, s83
	global_load_lds_dword v16, s[28:29]
	s_lshl_b64 s[28:29], s[18:19], 2
	s_add_u32 s28, s54, s28
	s_addc_u32 s29, s55, s29
	s_lshl_b64 s[18:19], s[18:19], 12
	s_waitcnt vmcnt(20)
	v_mov_b32_e32 v206, v197
	v_mov_b32_e32 v207, v196
	v_lshl_add_u64 v[80:81], v[182:183], 0, s[18:19]
	s_nop 0
	global_load_dword v196, v157, s[28:29]
	global_load_dword v197, v[80:81], off
	s_waitcnt vmcnt(16)
	ds_read_b128 v[76:79], v17 offset:512
	ds_read_b128 v[64:67], v17 offset:528
	ds_read_b64_tr_b8 v[240:241], v212
	ds_read_b64_tr_b8 v[242:243], v213
	ds_read_b64_tr_b8 v[244:245], v214
	ds_read_b64_tr_b8 v[246:247], v215
	ds_read_b64_tr_b8 v[248:249], v216
	ds_read_b64_tr_b8 v[250:251], v217
	ds_read_b64_tr_b8 v[252:253], v218
	ds_read_b64_tr_b8 v[228:229], v219
	s_waitcnt lgkmcnt(4)
	s_waitcnt vmcnt(12)
	ds_read_b64_tr_b8 v[48:49], v212 offset:4096
	ds_read_b64_tr_b8 v[50:51], v213 offset:4096
	ds_read_b64_tr_b8 v[52:53], v214 offset:4096
	ds_read_b64_tr_b8 v[54:55], v215 offset:4096
	v_dot4_i32_i8 v232, v240, v220, 0
	v_dot4_i32_i8 v233, v242, v220, 0
	v_dot4_i32_i8 v234, v244, v220, 0
	v_dot4_i32_i8 v235, v246, v220, 0
	v_dot4_i32_i8 v232, v241, v224, v232
	v_dot4_i32_i8 v233, v243, v224, v233
	v_dot4_i32_i8 v234, v245, v224, v234
	v_dot4_i32_i8 v235, v247, v224, v235
	s_waitcnt lgkmcnt(4)
	s_setprio 3
	v_mad_u32_u16 v80, v76, s58, v200 op_sel:[0,0,0,0]
	v_mad_u32_u16 v82, v76, s58, v201 op_sel:[1,0,0,0]
	s_add_i32 m0, s97, 0x0
	s_nop 0
	global_load_lds_dwordx4 v80, s[56:57]
	s_add_i32 m0, s97, 0x400
	s_nop 0
	global_load_lds_dwordx4 v82, s[56:57]
	v_mad_u32_u16 v80, v77, s58, v202 op_sel:[0,0,0,0]
	v_mad_u32_u16 v76, v77, s58, v203 op_sel:[1,0,0,0]
	s_add_i32 m0, s97, 0x800
	s_nop 0
	global_load_lds_dwordx4 v80, s[56:57]
	s_add_i32 m0, s97, 0xc00
	s_nop 0
	global_load_lds_dwordx4 v76, s[56:57]
	s_setprio 0
	ds_read_b64_tr_b8 v[240:241], v216 offset:4096
	ds_read_b64_tr_b8 v[242:243], v217 offset:4096
	ds_read_b64_tr_b8 v[244:245], v218 offset:4096
	ds_read_b64_tr_b8 v[246:247], v219 offset:4096
	v_dot4_i32_i8 v236, v248, v220, 0
	v_dot4_i32_i8 v237, v250, v220, 0
	v_dot4_i32_i8 v238, v252, v220, 0
	v_dot4_i32_i8 v239, v228, v220, 0
	v_dot4_i32_i8 v236, v249, v224, v236
	v_dot4_i32_i8 v237, v251, v224, v237
	v_dot4_i32_i8 v238, v253, v224, v238
	v_dot4_i32_i8 v239, v229, v224, v239
	s_waitcnt lgkmcnt(4)
	s_waitcnt vmcnt(12)
	ds_read_b64_tr_b8 v[248:249], v212 offset:8192
	ds_read_b64_tr_b8 v[250:251], v213 offset:8192
	ds_read_b64_tr_b8 v[252:253], v214 offset:8192
	ds_read_b64_tr_b8 v[228:229], v215 offset:8192
	v_dot4_i32_i8 v232, v48, v221, v232
	v_dot4_i32_i8 v233, v50, v221, v233
	v_dot4_i32_i8 v234, v52, v221, v234
	v_dot4_i32_i8 v235, v54, v221, v235
	v_dot4_i32_i8 v232, v49, v225, v232
	v_dot4_i32_i8 v233, v51, v225, v233
	v_dot4_i32_i8 v234, v53, v225, v234
	v_dot4_i32_i8 v235, v55, v225, v235
	s_waitcnt lgkmcnt(4)
	s_setprio 3
	v_mad_u32_u16 v76, v78, s58, v200 op_sel:[0,0,0,0]
	v_mad_u32_u16 v80, v78, s58, v201 op_sel:[1,0,0,0]
	s_add_i32 m0, s97, 0x1000
	s_nop 0
	global_load_lds_dwordx4 v76, s[56:57]
	s_add_i32 m0, s97, 0x1400
	s_nop 0
	global_load_lds_dwordx4 v80, s[56:57]
	v_mad_u32_u16 v76, v79, s58, v202 op_sel:[0,0,0,0]
	v_mad_u32_u16 v78, v79, s58, v203 op_sel:[1,0,0,0]
	s_add_i32 m0, s97, 0x1800
	s_nop 0
	global_load_lds_dwordx4 v76, s[56:57]
	s_add_i32 m0, s97, 0x1c00
	s_nop 0
	global_load_lds_dwordx4 v78, s[56:57]
	s_setprio 0
	ds_read_b64_tr_b8 v[48:49], v216 offset:8192
	ds_read_b64_tr_b8 v[50:51], v217 offset:8192
	ds_read_b64_tr_b8 v[52:53], v218 offset:8192
	ds_read_b64_tr_b8 v[54:55], v219 offset:8192
	v_dot4_i32_i8 v236, v240, v221, v236
	v_dot4_i32_i8 v237, v242, v221, v237
	v_dot4_i32_i8 v238, v244, v221, v238
	v_dot4_i32_i8 v239, v246, v221, v239
	v_dot4_i32_i8 v236, v241, v225, v236
	v_dot4_i32_i8 v237, v243, v225, v237
	v_dot4_i32_i8 v238, v245, v225, v238
	v_dot4_i32_i8 v239, v247, v225, v239
	s_waitcnt lgkmcnt(4)
	s_waitcnt vmcnt(12)
	ds_read_b64_tr_b8 v[240:241], v212 offset:12288
	ds_read_b64_tr_b8 v[242:243], v213 offset:12288
	ds_read_b64_tr_b8 v[244:245], v214 offset:12288
	ds_read_b64_tr_b8 v[246:247], v215 offset:12288
	v_dot4_i32_i8 v232, v248, v222, v232
	v_dot4_i32_i8 v233, v250, v222, v233
	v_dot4_i32_i8 v234, v252, v222, v234
	v_dot4_i32_i8 v235, v228, v222, v235
	v_dot4_i32_i8 v232, v249, v226, v232
	v_dot4_i32_i8 v233, v251, v226, v233
	v_dot4_i32_i8 v234, v253, v226, v234
	v_dot4_i32_i8 v235, v229, v226, v235
	s_waitcnt lgkmcnt(4)
; #define P7C_LOADA(R0, R1, C, S, X, t) do { const int tt_ = (t) < NT_TOK ? (t) : NT_TOK - 1; const unsigned char* rp_ = rp0 + (size_t)tt_ * 256; R0 = *(const v4u*)rp_; R1 = *(const v4u*)(rp_ + 16); \
;             C = *(const v4u*)(cp0 + (size_t)tt_ * 128); S = SCQ[tt_]; X = *(const unsigned*)(X2Bw + (size_t)tt_ * DM + 128 * hs + 16 * seg + 2 * r); } while (0)
; #define P7C_ISSUE(G, R0, R1) do { __builtin_amdgcn_s_setprio(3); _Pragma("unroll") for (int i_ = 0; i_ < 16; ++i_) { const unsigned e_ = P7_EID(R0, R1, i_); G[i_] = *(const v4u*)(Vb + (size_t)e_ * 128); } __builtin_amdgcn_s_setprio(0); } while (0)
; __device__ __forceinline__ void p7c_vaxpy(Frame& F, unsigned* bar, unsigned x, unsigned rank) {
;     ...
;         v4u GA[16], GB[16], ra0, ra1, ca, rb0, rb1, cb, cA, cB; float sa, sb, sA, sB; unsigned xa, xb2, xA, xB;
;         P7C_LOADA(ra0, ra1, ca, sa, xa, gwl);
;         P7C_LOADA(rb0, rb1, cb, sb, xb2, gwl + stride);
;         P7C_ISSUE(GA, ra0, ra1); cA = ca; sA = sa; xA = xa;
; #pragma unroll 1
;         for (int t = gwl; t < NT_TOK; t += 2 * stride) {
;             P7C_LOADA(ra0, ra1, ca, sa, xa, t + 2 * stride); P7C_ISSUE(GB, rb0, rb1); cB = cb; sB = sb; xB = xb2; P7C_COMP(GA, cA, sA, xA, t);
;             P7C_LOADA(rb0, rb1, cb, sb, xb2, t + 3 * stride); P7C_ISSUE(GA, ra0, ra1); cA = ca; sA = sa; xA = xa; P7C_COMP(GB, cB, sB, xB, t + stride);
	s_setprio 3
	v_mad_u32_u16 v76, v64, s58, v200 op_sel:[0,0,0,0]
	v_mad_u32_u16 v78, v64, s58, v201 op_sel:[1,0,0,0]
	s_add_i32 m0, s97, 0x2000
	s_nop 0
	global_load_lds_dwordx4 v76, s[56:57]
	s_add_i32 m0, s97, 0x2400
	s_nop 0
	global_load_lds_dwordx4 v78, s[56:57]
	v_mad_u32_u16 v76, v65, s58, v202 op_sel:[0,0,0,0]
	v_mad_u32_u16 v64, v65, s58, v203 op_sel:[1,0,0,0]
	s_add_i32 m0, s97, 0x2800
	s_nop 0
	global_load_lds_dwordx4 v76, s[56:57]
	s_add_i32 m0, s97, 0x2c00
	s_nop 0
	global_load_lds_dwordx4 v64, s[56:57]
	s_setprio 0
	ds_read_b64_tr_b8 v[248:249], v216 offset:12288
	ds_read_b64_tr_b8 v[250:251], v217 offset:12288
	ds_read_b64_tr_b8 v[252:253], v218 offset:12288
	ds_read_b64_tr_b8 v[228:229], v219 offset:12288
	v_dot4_i32_i8 v236, v48, v222, v236
	v_dot4_i32_i8 v237, v50, v222, v237
	v_dot4_i32_i8 v238, v52, v222, v238
	v_dot4_i32_i8 v239, v54, v222, v239
	v_dot4_i32_i8 v236, v49, v226, v236
	v_dot4_i32_i8 v237, v51, v226, v237
	v_dot4_i32_i8 v238, v53, v226, v238
	v_dot4_i32_i8 v239, v55, v226, v239
	s_waitcnt lgkmcnt(4)
	v_dot4_i32_i8 v232, v240, v223, v232
	v_dot4_i32_i8 v233, v242, v223, v233
	v_dot4_i32_i8 v234, v244, v223, v234
	v_dot4_i32_i8 v235, v246, v223, v235
	v_dot4_i32_i8 v232, v241, v227, v232
	v_dot4_i32_i8 v233, v243, v227, v233
	v_dot4_i32_i8 v234, v245, v227, v234
	v_dot4_i32_i8 v235, v247, v227, v235
	s_waitcnt lgkmcnt(0)
	s_setprio 3
	v_mad_u32_u16 v64, v66, s58, v200 op_sel:[0,0,0,0]
	v_mad_u32_u16 v76, v66, s58, v201 op_sel:[1,0,0,0]
	s_add_i32 m0, s97, 0x3000
	s_nop 0
	global_load_lds_dwordx4 v64, s[56:57]
	s_add_i32 m0, s97, 0x3400
	s_nop 0
	global_load_lds_dwordx4 v76, s[56:57]
	v_mad_u32_u16 v64, v67, s58, v202 op_sel:[0,0,0,0]
	v_mad_u32_u16 v66, v67, s58, v203 op_sel:[1,0,0,0]
	s_add_i32 m0, s97, 0x3800
	s_nop 0
	global_load_lds_dwordx4 v64, s[56:57]
	s_add_i32 m0, s97, 0x3c00
	s_nop 0
	global_load_lds_dwordx4 v66, s[56:57]
	s_setprio 0
	v_dot4_i32_i8 v236, v248, v223, v236
	v_dot4_i32_i8 v237, v250, v223, v237
	v_dot4_i32_i8 v238, v252, v223, v238
	v_dot4_i32_i8 v239, v228, v223, v239
	v_dot4_i32_i8 v236, v249, v227, v236
	v_dot4_i32_i8 v237, v251, v227, v237
	v_dot4_i32_i8 v238, v253, v227, v238
	v_dot4_i32_i8 v239, v229, v227, v239
	s_nop 2
	v_permlane32_swap_b32_e32 v232, v236
	v_permlane32_swap_b32_e32 v233, v237
	v_permlane32_swap_b32_e32 v234, v238
	v_permlane32_swap_b32_e32 v235, v239
	v_add_u32_e32 v232, v232, v236
	v_add_u32_e32 v233, v233, v237
	v_add_u32_e32 v234, v234, v238
	v_add_u32_e32 v235, v235, v239
	s_nop 1
	v_permlane16_swap_b32_e32 v232, v234
	v_permlane16_swap_b32_e32 v233, v235
	v_add_u32_e32 v232, v232, v234
	v_add_u32_e32 v233, v233, v235
	s_nop 1
	v_mov_b32_dpp v234, v232 quad_perm:[1,0,3,2] row_mask:0xf bank_mask:0xf
	v_mov_b32_dpp v235, v233 quad_perm:[1,0,3,2] row_mask:0xf bank_mask:0xf
	v_cndmask_b32_e64 v236, v235, v232, s[44:45]
	v_cndmask_b32_e64 v237, v233, v234, s[44:45]
	v_cvt_f32_i32_e32 v236, v236
	v_cvt_f32_i32_e32 v237, v237
	v_lshlrev_b32_e32 v238, 16, v206
	v_and_b32_e32 v239, 0xffff0000, v206
	v_fmac_f32_e32 v238, v207, v236
	v_fmac_f32_e32 v239, v207, v237
	v_mul_f32_e32 v240, v239, v239
	v_fmac_f32_e32 v240, v238, v238
	v_cvt_pk_bf16_f32 v244, v238, v239
	global_store_dword v[188:189], v244, off
	s_nop 1
	v_add_f32_dpp v240, v240, v240 quad_perm:[1,0,3,2] row_mask:0xf bank_mask:0xf
	s_nop 1
	v_add_f32_dpp v240, v240, v240 quad_perm:[2,3,0,1] row_mask:0xf bank_mask:0xf
	s_nop 1
	v_add_f32_dpp v240, v240, v240 row_half_mirror row_mask:0xf bank_mask:0xf
	s_nop 1
	v_add_f32_dpp v240, v240, v240 row_mirror row_mask:0xf bank_mask:0xf
	v_mov_b32_e32 v242, v240
	s_nop 1
	v_permlane16_swap_b32_e32 v240, v242
	v_add_f32_e32 v240, v240, v242
	v_mov_b32_e32 v242, v240
	s_nop 1
	v_permlane32_swap_b32_e32 v240, v242
	v_add_f32_e32 v240, v240, v242
	s_and_saveexec_b64 s[18:19], s[42:43]
	s_cbranch_execz .LBB0_1091
	global_store_dword v[186:187], v240, off
.LBB0_1091:
	s_or_b64 exec, exec, s[18:19]
	s_add_i32 s18, s24, s20
	s_min_i32 s18, s18, 0x5fff
	s_ashr_i32 s19, s18, 31
	s_lshl_b64 s[28:29], s[18:19], 8
	s_waitcnt lgkmcnt(0)
	s_waitcnt vmcnt(24)
	ds_read_b128 v[220:223], v18 offset:768
	ds_read_b128 v[224:227], v18 offset:784
	s_waitcnt lgkmcnt(0)
	s_add_i32 m0, s59, 0x200
	s_add_u32 s28, s28, s60
	s_addc_u32 s29, s29, s61
	global_load_lds_dword v16, s[28:29]
	s_lshl_b64 s[28:29], s[18:19], 7
	s_add_i32 m0, s59, 0x300
	s_add_u32 s28, s28, s82
	s_addc_u32 s29, s29, s83
	global_load_lds_dword v16, s[28:29]
	s_lshl_b64 s[28:29], s[18:19], 2
	s_add_u32 s28, s54, s28
	s_addc_u32 s29, s55, s29
	s_lshl_b64 s[18:19], s[18:19], 12
	v_lshl_add_u64 v[10:11], v[182:183], 0, s[18:19]
	global_load_dword v207, v157, s[28:29]
	global_load_dword v206, v[10:11], off
	s_waitcnt vmcnt(17)
	ds_read_b128 v[148:151], v17
	ds_read_b128 v[144:147], v17 offset:16
	ds_read_b64_tr_b8 v[240:241], v212
	ds_read_b64_tr_b8 v[242:243], v213
	ds_read_b64_tr_b8 v[244:245], v214
	ds_read_b64_tr_b8 v[246:247], v215
	ds_read_b64_tr_b8 v[248:249], v216
	ds_read_b64_tr_b8 v[250:251], v217
	ds_read_b64_tr_b8 v[252:253], v218
	ds_read_b64_tr_b8 v[228:229], v219
	s_waitcnt lgkmcnt(4)
	s_waitcnt vmcnt(13)
	ds_read_b64_tr_b8 v[128:129], v212 offset:4096
	ds_read_b64_tr_b8 v[130:131], v213 offset:4096
	ds_read_b64_tr_b8 v[132:133], v214 offset:4096
	ds_read_b64_tr_b8 v[134:135], v215 offset:4096
	v_dot4_i32_i8 v232, v240, v220, 0
	v_dot4_i32_i8 v233, v242, v220, 0
	v_dot4_i32_i8 v234, v244, v220, 0
	v_dot4_i32_i8 v235, v246, v220, 0
	v_dot4_i32_i8 v232, v241, v224, v232
	v_dot4_i32_i8 v233, v243, v224, v233
	v_dot4_i32_i8 v234, v245, v224, v234
	v_dot4_i32_i8 v235, v247, v224, v235
	s_waitcnt lgkmcnt(4)
	s_setprio 3
	v_mad_u32_u16 v8, v148, s58, v200 op_sel:[0,0,0,0]
	v_mad_u32_u16 v10, v148, s58, v201 op_sel:[1,0,0,0]
	s_add_i32 m0, s97, 0x0
	s_nop 0
	global_load_lds_dwordx4 v8, s[56:57]
	s_add_i32 m0, s97, 0x400
	s_nop 0
	global_load_lds_dwordx4 v10, s[56:57]
	v_mad_u32_u16 v8, v149, s58, v202 op_sel:[0,0,0,0]
	v_mad_u32_u16 v10, v149, s58, v203 op_sel:[1,0,0,0]
	s_add_i32 m0, s97, 0x800
	s_nop 0
	global_load_lds_dwordx4 v8, s[56:57]
	s_add_i32 m0, s97, 0xc00
	s_nop 0
	global_load_lds_dwordx4 v10, s[56:57]
	s_setprio 0
	ds_read_b64_tr_b8 v[240:241], v216 offset:4096
	ds_read_b64_tr_b8 v[242:243], v217 offset:4096
	ds_read_b64_tr_b8 v[244:245], v218 offset:4096
	ds_read_b64_tr_b8 v[246:247], v219 offset:4096
	v_dot4_i32_i8 v236, v248, v220, 0
	v_dot4_i32_i8 v237, v250, v220, 0
	v_dot4_i32_i8 v238, v252, v220, 0
	v_dot4_i32_i8 v239, v228, v220, 0
	v_dot4_i32_i8 v236, v249, v224, v236
	v_dot4_i32_i8 v237, v251, v224, v237
	v_dot4_i32_i8 v238, v253, v224, v238
	v_dot4_i32_i8 v239, v229, v224, v239
	s_waitcnt lgkmcnt(4)
	s_waitcnt vmcnt(13)
	ds_read_b64_tr_b8 v[248:249], v212 offset:8192
	ds_read_b64_tr_b8 v[250:251], v213 offset:8192
	ds_read_b64_tr_b8 v[252:253], v214 offset:8192
	ds_read_b64_tr_b8 v[228:229], v215 offset:8192
	v_dot4_i32_i8 v232, v128, v221, v232
	v_dot4_i32_i8 v233, v130, v221, v233
	v_dot4_i32_i8 v234, v132, v221, v234
	v_dot4_i32_i8 v235, v134, v221, v235
	v_dot4_i32_i8 v232, v129, v225, v232
	v_dot4_i32_i8 v233, v131, v225, v233
	v_dot4_i32_i8 v234, v133, v225, v234
	v_dot4_i32_i8 v235, v135, v225, v235
	s_waitcnt lgkmcnt(4)
	s_setprio 3
	v_mad_u32_u16 v8, v150, s58, v200 op_sel:[0,0,0,0]
	v_mad_u32_u16 v10, v150, s58, v201 op_sel:[1,0,0,0]
	s_add_i32 m0, s97, 0x1000
	s_nop 0
	global_load_lds_dwordx4 v8, s[56:57]
	s_add_i32 m0, s97, 0x1400
	s_nop 0
	global_load_lds_dwordx4 v10, s[56:57]
	v_mad_u32_u16 v8, v151, s58, v202 op_sel:[0,0,0,0]
	v_mad_u32_u16 v10, v151, s58, v203 op_sel:[1,0,0,0]
	s_add_i32 m0, s97, 0x1800
	s_nop 0
	global_load_lds_dwordx4 v8, s[56:57]
	s_add_i32 m0, s97, 0x1c00
	s_nop 0
	global_load_lds_dwordx4 v10, s[56:57]
	s_setprio 0
	ds_read_b64_tr_b8 v[128:129], v216 offset:8192
	ds_read_b64_tr_b8 v[130:131], v217 offset:8192
	ds_read_b64_tr_b8 v[132:133], v218 offset:8192
	ds_read_b64_tr_b8 v[134:135], v219 offset:8192
	v_dot4_i32_i8 v236, v240, v221, v236
	v_dot4_i32_i8 v237, v242, v221, v237
	v_dot4_i32_i8 v238, v244, v221, v238
	v_dot4_i32_i8 v239, v246, v221, v239
	v_dot4_i32_i8 v236, v241, v225, v236
	v_dot4_i32_i8 v237, v243, v225, v237
	v_dot4_i32_i8 v238, v245, v225, v238
	v_dot4_i32_i8 v239, v247, v225, v239
	s_waitcnt lgkmcnt(4)
	s_waitcnt vmcnt(13)
	ds_read_b64_tr_b8 v[240:241], v212 offset:12288
	ds_read_b64_tr_b8 v[242:243], v213 offset:12288
	ds_read_b64_tr_b8 v[244:245], v214 offset:12288
	ds_read_b64_tr_b8 v[246:247], v215 offset:12288
	v_dot4_i32_i8 v232, v248, v222, v232
	v_dot4_i32_i8 v233, v250, v222, v233
	v_dot4_i32_i8 v234, v252, v222, v234
	v_dot4_i32_i8 v235, v228, v222, v235
	v_dot4_i32_i8 v232, v249, v226, v232
	v_dot4_i32_i8 v233, v251, v226, v233
	v_dot4_i32_i8 v234, v253, v226, v234
	v_dot4_i32_i8 v235, v229, v226, v235
	s_waitcnt lgkmcnt(4)
	s_setprio 3
	v_mad_u32_u16 v8, v144, s58, v200 op_sel:[0,0,0,0]
	v_mad_u32_u16 v10, v144, s58, v201 op_sel:[1,0,0,0]
	s_add_i32 m0, s97, 0x2000
	s_nop 0
	global_load_lds_dwordx4 v8, s[56:57]
	s_add_i32 m0, s97, 0x2400
	s_nop 0
	global_load_lds_dwordx4 v10, s[56:57]
	v_mad_u32_u16 v8, v145, s58, v202 op_sel:[0,0,0,0]
	v_mad_u32_u16 v10, v145, s58, v203 op_sel:[1,0,0,0]
	s_add_i32 m0, s97, 0x2800
	s_nop 0
	global_load_lds_dwordx4 v8, s[56:57]
	s_add_i32 m0, s97, 0x2c00
	s_nop 0
	global_load_lds_dwordx4 v10, s[56:57]
	s_setprio 0
	ds_read_b64_tr_b8 v[248:249], v216 offset:12288
	ds_read_b64_tr_b8 v[250:251], v217 offset:12288
	ds_read_b64_tr_b8 v[252:253], v218 offset:12288
	ds_read_b64_tr_b8 v[228:229], v219 offset:12288
	v_dot4_i32_i8 v236, v128, v222, v236
	v_dot4_i32_i8 v237, v130, v222, v237
	v_dot4_i32_i8 v238, v132, v222, v238
	v_dot4_i32_i8 v239, v134, v222, v239
	v_dot4_i32_i8 v236, v129, v226, v236
	v_dot4_i32_i8 v237, v131, v226, v237
	v_dot4_i32_i8 v238, v133, v226, v238
	v_dot4_i32_i8 v239, v135, v226, v239
	s_waitcnt lgkmcnt(4)
	v_dot4_i32_i8 v232, v240, v223, v232
	v_dot4_i32_i8 v233, v242, v223, v233
	v_dot4_i32_i8 v234, v244, v223, v234
	v_dot4_i32_i8 v235, v246, v223, v235
	v_dot4_i32_i8 v232, v241, v227, v232
	v_dot4_i32_i8 v233, v243, v227, v233
	v_dot4_i32_i8 v234, v245, v227, v234
	v_dot4_i32_i8 v235, v247, v227, v235
	s_waitcnt lgkmcnt(0)
	s_setprio 3
	v_mad_u32_u16 v8, v146, s58, v200 op_sel:[0,0,0,0]
	v_mad_u32_u16 v12, v146, s58, v201 op_sel:[1,0,0,0]
	v_mad_u32_u16 v24, v147, s58, v202 op_sel:[0,0,0,0]
	v_mad_u32_u16 v28, v147, s58, v203 op_sel:[1,0,0,0]
	s_add_i32 m0, s97, 0x3000
	s_nop 0
	global_load_lds_dwordx4 v8, s[56:57]
	s_nop 0
	s_add_i32 m0, s97, 0x3400
	s_nop 0
	global_load_lds_dwordx4 v12, s[56:57]
	s_nop 0
	s_add_i32 m0, s97, 0x3800
	s_nop 0
	global_load_lds_dwordx4 v24, s[56:57]
	s_nop 0
	s_add_i32 m0, s97, 0x3c00
	s_nop 0
	global_load_lds_dwordx4 v28, s[56:57]
	s_setprio 0
	v_dot4_i32_i8 v236, v248, v223, v236
	v_dot4_i32_i8 v237, v250, v223, v237
	v_dot4_i32_i8 v238, v252, v223, v238
	v_dot4_i32_i8 v239, v228, v223, v239
	v_dot4_i32_i8 v236, v249, v227, v236
	v_dot4_i32_i8 v237, v251, v227, v237
	v_dot4_i32_i8 v238, v253, v227, v238
	v_dot4_i32_i8 v239, v229, v227, v239
	s_nop 2
	v_permlane32_swap_b32_e32 v232, v236
	v_permlane32_swap_b32_e32 v233, v237
	v_permlane32_swap_b32_e32 v234, v238
	v_permlane32_swap_b32_e32 v235, v239
	v_add_u32_e32 v232, v232, v236
	v_add_u32_e32 v233, v233, v237
	v_add_u32_e32 v234, v234, v238
	v_add_u32_e32 v235, v235, v239
	s_nop 1
	v_permlane16_swap_b32_e32 v232, v234
	v_permlane16_swap_b32_e32 v233, v235
	v_add_u32_e32 v232, v232, v234
	v_add_u32_e32 v233, v233, v235
	s_nop 1
	v_mov_b32_dpp v234, v232 quad_perm:[1,0,3,2] row_mask:0xf bank_mask:0xf
	v_mov_b32_dpp v235, v233 quad_perm:[1,0,3,2] row_mask:0xf bank_mask:0xf
	v_cndmask_b32_e64 v236, v235, v232, s[44:45]
	v_cndmask_b32_e64 v237, v233, v234, s[44:45]
	v_cvt_f32_i32_e32 v236, v236
	v_cvt_f32_i32_e32 v237, v237
	v_lshlrev_b32_e32 v4, 16, v199
	v_and_b32_e32 v5, 0xffff0000, v199
	v_fmac_f32_e32 v4, v198, v236
	v_fmac_f32_e32 v5, v198, v237
	v_mul_f32_e32 v6, v5, v5
	v_fmac_f32_e32 v6, v4, v4
	s_nop 1
	v_add_f32_dpp v6, v6, v6 quad_perm:[1,0,3,2] row_mask:0xf bank_mask:0xf
	s_nop 1
	v_add_f32_dpp v6, v6, v6 quad_perm:[2,3,0,1] row_mask:0xf bank_mask:0xf
	s_nop 1
	v_add_f32_dpp v6, v6, v6 row_half_mirror row_mask:0xf bank_mask:0xf
	s_nop 1
	v_add_f32_dpp v6, v6, v6 row_mirror row_mask:0xf bank_mask:0xf
	v_mov_b32_e32 v7, v6
	s_nop 1
	v_permlane16_swap_b32_e32 v6, v7
	v_add_f32_e32 v6, v6, v7
	v_mov_b32_e32 v7, v6
	s_nop 1
	v_permlane32_swap_b32_e32 v6, v7
	v_add_f32_e32 v6, v6, v7
	s_add_i32 s18, s23, s20
	s_cmpk_gt_i32 s18, 0x5fff
	s_cbranch_scc1 .LBB0_1088
	s_ashr_i32 s19, s18, 31
	s_lshl_b64 s[20:21], s[18:19], 12
	v_lshl_add_u64 v[80:81], v[182:183], 0, s[20:21]
	v_cvt_pk_bf16_f32 v4, v4, v5
	global_store_dword v[80:81], v4, off
	s_and_saveexec_b64 s[20:21], s[42:43]
	s_cbranch_execz .LBB0_1087
	s_lshl_b64 s[18:19], s[18:19], 6
	v_lshl_add_u64 v[4:5], v[184:185], 0, s[18:19]
	global_store_dword v[4:5], v6, off
	s_branch .LBB0_1087
